# norm loops: per-chunk modulation-vector loads hoisted to the iteration top (fresh regs, one wait) on top of early-wait removal; on v91
# baseline (speedup 1.0000x reference)
; #define GAS __attribute__((address_space(1)))
; __device__ __forceinline__ float sumsq8(const u32x4 w) { const f32x4 a = unpack_lo4(w), b = unpack_hi4(w); return ((a.x * a.x + a.y * a.y) + (a.z * a.z + a.w * a.w)) + ((b.x * b.x + b.y * b.y) + (b.z * b.z + b.w * b.w)); }
; #define KARG(f) (kargp[opaque_zero()].f)
; template <int R> __device__ __forceinline__ void norm_rows_bf16in(const bf16* x, bf16* o, int m0, int rstride, const float* g, const float* shift, const float* scale, int lane) {
;     u32x4 v[R][2]; float s[R];
; #pragma unroll
;     for (int r = 0; r < R; ++r) { const GAS u32x4* xr = (const GAS u32x4*)(x + (size_t)(m0 + r * rstride) * D) + lane; v[r][0] = __builtin_nontemporal_load(xr); v[r][1] = __builtin_nontemporal_load(xr + 64); }
; #pragma unroll
;     for (int r = 0; r < R; ++r) { s[r] = 0.f;
; #pragma unroll
;         for (int j = 0; j < 2; ++j) s[r] += sumsq8(v[r][j]); }
; #pragma unroll
;     for (int of = 1; of < 64; of <<= 1) {
; #pragma unroll
;         for (int r = 0; r < R; ++r) s[r] += __shfl_xor(s[r], of); }
; __global__ void __launch_bounds__(NWAVES * 64, 2) fwd_megakernel(Args a_unused) {
;     ...
;             } else { const bf16* xs = (const bf16*)(wsl + WS_XS);
;                 for (int it = 0, m = gw; it < M / (4 * NGW); ++it, m += 4 * NGW) {
;                     const float* mb = modl + (m >> 13) * NMOD + step * 3072;
;                     norm_rows_bf16in<4>(xs, XNl, m, NGW, KARG(g_norm) + step * D, mb, mb + 1024, ln); }
.LBB0_124:
	v_cmp_lt_i32_e32 vcc, v214, v213
	s_add_i32 s8, s16, s14
	s_mov_b32 s4, 0
	v_cndmask_b32_e32 v0, v212, v214, vcc
	v_cmp_lt_i32_e32 vcc, v215, v213
	v_lshl_add_u64 v[22:23], s[72:73], 0, v[74:75]
	global_load_dwordx4 v[18:21], v[22:23], off offset:1024 nt
	global_load_dwordx4 v[14:17], v[22:23], off nt
	v_cndmask_b32_e32 v5, v212, v215, vcc
	v_cmp_lt_i32_e32 vcc, v216, v213
	s_ashr_i32 s5, s8, 13
	s_brev_b32 s6, 7
	v_cndmask_b32_e32 v6, v212, v216, vcc
	v_cmp_lt_i32_e32 vcc, v217, v213
	s_mul_hi_i32 s9, s4, 0xc8
	s_mul_i32 s10, s4, 0xc8
	v_cndmask_b32_e32 v7, v212, v217, vcc
	v_cmp_lt_i32_e32 vcc, v218, v213
	v_lshlrev_b32_e32 v145, 2, v0
	v_lshlrev_b32_e32 v144, 2, v5
	v_cndmask_b32_e32 v8, v212, v218, vcc
	v_cmp_lt_i32_e32 vcc, v219, v213
	v_lshlrev_b32_e32 v143, 2, v6
	v_lshlrev_b32_e32 v142, 2, v7
	v_cndmask_b32_e32 v9, v212, v219, vcc
	v_add_co_u32_e32 v26, vcc, s6, v22
	s_mul_i32 s6, s5, 0x2400
	s_ashr_i32 s7, s6, 31
	s_lshl_b64 s[4:5], s[6:7], 2
	s_add_u32 s4, s13, s4
	s_addc_u32 s5, s18, s5
	s_add_u32 s6, s0, s10
	v_lshl_add_u64 v[24:25], s[4:5], 0, v[76:77]
	s_addc_u32 s7, s1, s9
	v_lshlrev_b32_e32 v5, 2, v8
	v_lshlrev_b32_e32 v0, 2, v9
	global_load_dwordx4 v[6:9], v[24:25], off offset:16
	global_load_dwordx4 v[10:13], v[24:25], off
	s_load_dwordx2 s[6:7], s[6:7], 0x20
	v_lshl_add_u64 v[28:29], s[4:5], 0, v[78:79]
	v_addc_co_u32_e32 v27, vcc, -1, v23, vcc
	s_waitcnt lgkmcnt(0)
	s_add_u32 s6, s6, s70
	s_addc_u32 s7, s7, s71
	s_add_u32 s4, s4, 0x1000
	v_lshl_add_u64 v[30:31], s[6:7], 0, v[76:77]
	v_lshl_add_u64 v[62:63], s[6:7], 0, v[78:79]
	s_addc_u32 s5, s5, 0
	s_add_i32 s6, s8, 0x800
	s_ashr_i32 s7, s6, 31
	v_lshl_add_u64 v[72:73], s[4:5], 0, v[76:77]
	s_nop 0
	v_lshl_add_u64 v[80:81], s[4:5], 0, v[78:79]
	s_lshl_b64 s[4:5], s[6:7], 11
	s_add_u32 s6, s56, s4
	s_addc_u32 s7, s57, s5
	s_add_i32 s10, s8, 0x1000
	global_load_dwordx4 v[48:51], v[30:31], off offset:16
	global_load_dwordx4 v[52:55], v[30:31], off
	global_load_dwordx4 v[56:59], v[72:73], off
	global_load_dwordx4 v[64:67], v[72:73], off offset:16
	v_lshl_add_u64 v[32:33], s[6:7], 0, v[74:75]
	s_ashr_i32 s11, s10, 31
	global_load_dwordx4 v[68:71], v[32:33], off offset:1024 nt
	global_load_dwordx4 v[82:85], v[32:33], off nt
	s_lshl_b64 s[6:7], s[10:11], 11
	s_add_u32 s10, s56, s6
	s_addc_u32 s11, s57, s7
	s_addk_i32 s8, 0x1800
	v_lshl_add_u64 v[32:33], s[10:11], 0, v[74:75]
	s_ashr_i32 s9, s8, 31
	global_load_dwordx4 v[88:91], v[32:33], off nt
	global_load_dwordx4 v[92:95], v[32:33], off offset:1024 nt
	s_lshl_b64 s[8:9], s[8:9], 11
	s_add_u32 s10, s56, s8
	s_addc_u32 s11, s57, s9
	v_lshl_add_u64 v[32:33], s[10:11], 0, v[74:75]
	global_load_dwordx4 v[138:141], v[32:33], off nt
	global_load_dwordx4 v[146:149], v[32:33], off offset:1024 nt
	global_load_dwordx4 v[160:163], v[72:73], off offset:2048
	global_load_dwordx4 v[164:167], v[80:81], off offset:16
	global_load_dwordx4 v[168:171], v[30:31], off offset:2048
	global_load_dwordx4 v[172:175], v[62:63], off offset:16
	global_load_dwordx4 v[176:179], v[24:25], off offset:2048
	global_load_dwordx4 v[180:183], v[28:29], off offset:16
	s_add_u32 s4, s62, s4
	s_addc_u32 s5, s63, s5
	v_lshl_add_u64 v[32:33], s[4:5], 0, v[74:75]
	s_add_u32 s4, s62, s6
	s_addc_u32 s5, s63, s7
	v_lshl_add_u64 v[34:35], s[4:5], 0, v[74:75]
	s_add_u32 s4, s62, s8
	s_addc_u32 s5, s63, s9
	v_lshl_add_u64 v[36:37], s[4:5], 0, v[74:75]
	s_addk_i32 s14, 0x2000
	s_add_u32 s72, s72, 0x1000000
	s_addc_u32 s73, s73, 0
	s_waitcnt vmcnt(0)
	v_lshlrev_b32_e32 v41, 16, v18
	v_lshlrev_b32_e32 v40, 16, v14
	v_and_b32_e32 v39, 0xffff0000, v18
	v_and_b32_e32 v38, 0xffff0000, v14
	v_lshlrev_b32_e32 v43, 16, v19
	v_lshlrev_b32_e32 v42, 16, v15
	v_and_b32_e32 v19, 0xffff0000, v19
	v_and_b32_e32 v18, 0xffff0000, v15
	v_lshlrev_b32_e32 v45, 16, v20
	v_and_b32_e32 v15, 0xffff0000, v20
	v_and_b32_e32 v14, 0xffff0000, v16
	v_lshlrev_b32_e32 v47, 16, v21
	v_and_b32_e32 v21, 0xffff0000, v21
	v_and_b32_e32 v20, 0xffff0000, v17
	v_lshlrev_b32_e32 v44, 16, v16
	v_lshlrev_b32_e32 v46, 16, v17
	v_pk_mul_f32 v[16:17], v[38:39], v[38:39]
	v_pk_mul_f32 v[60:61], v[18:19], v[18:19]
	v_pk_mul_f32 v[86:87], v[14:15], v[14:15]
	v_pk_mul_f32 v[96:97], v[20:21], v[20:21]
	v_pk_fma_f32 v[16:17], v[40:41], v[40:41], v[16:17]
	v_pk_fma_f32 v[60:61], v[42:43], v[42:43], v[60:61]
	v_pk_fma_f32 v[86:87], v[44:45], v[44:45], v[86:87]
	v_pk_fma_f32 v[96:97], v[46:47], v[46:47], v[96:97]
	v_pk_add_f32 v[16:17], v[16:17], v[60:61]
	v_pk_add_f32 v[60:61], v[86:87], v[96:97]
	v_mov_b32_e32 v129, v14
	v_pk_add_f32 v[16:17], v[16:17], v[60:61]
	v_mov_b32_e32 v135, v18
	v_add_f32_e32 v14, v16, v17
	ds_bpermute_b32 v16, v145, v14
	v_mov_b32_e32 v131, v20
	v_mov_b32_e32 v133, v38
	v_mov_b32_e32 v132, v40
	v_mov_b32_e32 v134, v42
	s_waitcnt lgkmcnt(0)
	v_add_f32_e32 v14, v14, v16
	ds_bpermute_b32 v16, v144, v14
	v_mov_b32_e32 v128, v44
	v_mov_b32_e32 v130, v46
	s_cmp_lg_u32 s14, 0x10000
	s_waitcnt lgkmcnt(0)
	v_add_f32_e32 v14, v14, v16
	ds_bpermute_b32 v18, v143, v14
	s_waitcnt lgkmcnt(0)
; #define GAS __attribute__((address_space(1)))
; __device__ __forceinline__ float sumsq8(const u32x4 w) { const f32x4 a = unpack_lo4(w), b = unpack_hi4(w); return ((a.x * a.x + a.y * a.y) + (a.z * a.z + a.w * a.w)) + ((b.x * b.x + b.y * b.y) + (b.z * b.z + b.w * b.w)); }
; template <int R> __device__ __forceinline__ void norm_rows_bf16in(const bf16* x, bf16* o, int m0, int rstride, const float* g, const float* shift, const float* scale, int lane) {
;     ...
;     for (int r = 0; r < R; ++r) { s[r] = 0.f;
; #pragma unroll
;         for (int j = 0; j < 2; ++j) s[r] += sumsq8(v[r][j]); }
; #pragma unroll
;     for (int of = 1; of < 64; of <<= 1) {
; #pragma unroll
;         for (int r = 0; r < R; ++r) s[r] += __shfl_xor(s[r], of); }
; #pragma unroll
;     for (int j = 0; j < 2; ++j) {
;         const int i4 = 2 * (lane + 64 * j);
;         const f32x4 g0 = ((const GAS f32x4*)g)[i4], g1 = ((const GAS f32x4*)g)[i4 + 1], h0 = ((const GAS f32x4*)shift)[i4], h1 = ((const GAS f32x4*)shift)[i4 + 1], c0 = ((const GAS f32x4*)scale)[i4], c1 = ((const GAS f32x4*)scale)[i4 + 1];
;         const f32x4 gs0 = g0 * (c0 + 1.0f), gs1 = g1 * (c1 + 1.0f);
; #pragma unroll
;         for (int r = 0; r < R; ++r) {
;             const float rstd = 1.0f / sqrtf(s[r] * (1.0f / D) + EPS);
	v_add_f32_e32 v14, v14, v18
	v_pk_add_f32 v[16:17], v[58:59], 1.0 op_sel_hi:[1,0]
	v_pk_add_f32 v[56:57], v[56:57], 1.0 op_sel_hi:[1,0]
	v_pk_add_f32 v[58:59], v[66:67], 1.0 op_sel_hi:[1,0]
	v_pk_add_f32 v[60:61], v[64:65], 1.0 op_sel_hi:[1,0]
	v_pk_mul_f32 v[106:107], v[54:55], v[16:17]
	v_pk_mul_f32 v[108:109], v[52:53], v[56:57]
	v_pk_mul_f32 v[110:111], v[50:51], v[58:59]
	v_pk_mul_f32 v[112:113], v[48:49], v[60:61]
	v_and_b32_e32 v17, 0xffff0000, v68
	v_and_b32_e32 v16, 0xffff0000, v82
	v_and_b32_e32 v49, 0xffff0000, v69
	v_and_b32_e32 v48, 0xffff0000, v83
	v_and_b32_e32 v51, 0xffff0000, v70
	v_and_b32_e32 v50, 0xffff0000, v84
	v_and_b32_e32 v53, 0xffff0000, v71
	v_and_b32_e32 v52, 0xffff0000, v85
	v_lshlrev_b32_e32 v55, 16, v68
	v_lshlrev_b32_e32 v54, 16, v82
	v_lshlrev_b32_e32 v57, 16, v69
	v_lshlrev_b32_e32 v56, 16, v83
	v_lshlrev_b32_e32 v59, 16, v70
	v_lshlrev_b32_e32 v58, 16, v84
	v_lshlrev_b32_e32 v61, 16, v71
	v_lshlrev_b32_e32 v60, 16, v85
	v_pk_mul_f32 v[64:65], v[16:17], v[16:17]
	v_pk_mul_f32 v[66:67], v[48:49], v[48:49]
	v_pk_mul_f32 v[68:69], v[50:51], v[50:51]
	v_pk_mul_f32 v[70:71], v[52:53], v[52:53]
	v_mov_b32_e32 v115, v16
	v_pk_fma_f32 v[64:65], v[54:55], v[54:55], v[64:65]
	v_pk_fma_f32 v[66:67], v[56:57], v[56:57], v[66:67]
	v_pk_fma_f32 v[68:69], v[58:59], v[58:59], v[68:69]
	v_pk_fma_f32 v[70:71], v[60:61], v[60:61], v[70:71]
	ds_bpermute_b32 v16, v142, v14
	v_pk_add_f32 v[64:65], v[64:65], v[66:67]
	v_pk_add_f32 v[66:67], v[68:69], v[70:71]
	v_and_b32_e32 v69, 0xffff0000, v94
	v_pk_add_f32 v[96:97], v[64:65], v[66:67]
	v_and_b32_e32 v65, 0xffff0000, v92
	v_and_b32_e32 v64, 0xffff0000, v88
	v_and_b32_e32 v67, 0xffff0000, v93
	v_and_b32_e32 v66, 0xffff0000, v89
	v_and_b32_e32 v68, 0xffff0000, v90
	v_and_b32_e32 v71, 0xffff0000, v95
	v_and_b32_e32 v70, 0xffff0000, v91
	v_lshlrev_b32_e32 v83, 16, v92
	v_lshlrev_b32_e32 v82, 16, v88
	v_lshlrev_b32_e32 v85, 16, v93
	v_lshlrev_b32_e32 v84, 16, v89
	v_lshlrev_b32_e32 v87, 16, v94
	v_lshlrev_b32_e32 v86, 16, v90
	v_lshlrev_b32_e32 v89, 16, v95
	v_lshlrev_b32_e32 v88, 16, v91
	v_add_f32_e32 v18, v96, v97
	v_pk_mul_f32 v[90:91], v[64:65], v[64:65]
	v_pk_mul_f32 v[92:93], v[66:67], v[66:67]
	v_pk_mul_f32 v[94:95], v[68:69], v[68:69]
	v_pk_mul_f32 v[96:97], v[70:71], v[70:71]
	v_pk_fma_f32 v[90:91], v[82:83], v[82:83], v[90:91]
	v_pk_fma_f32 v[92:93], v[84:85], v[84:85], v[92:93]
	v_pk_fma_f32 v[94:95], v[86:87], v[86:87], v[94:95]
	v_pk_fma_f32 v[96:97], v[88:89], v[88:89], v[96:97]
	ds_bpermute_b32 v20, v145, v18
	v_pk_add_f32 v[90:91], v[90:91], v[92:93]
	v_pk_add_f32 v[92:93], v[94:95], v[96:97]
	s_waitcnt lgkmcnt(1)
	v_add_f32_e32 v14, v14, v16
	v_pk_add_f32 v[150:151], v[90:91], v[92:93]
	ds_bpermute_b32 v16, v5, v14
	v_and_b32_e32 v91, 0xffff0000, v146
	v_and_b32_e32 v90, 0xffff0000, v138
	v_and_b32_e32 v93, 0xffff0000, v147
	v_and_b32_e32 v92, 0xffff0000, v139
	v_and_b32_e32 v95, 0xffff0000, v148
	v_and_b32_e32 v94, 0xffff0000, v140
	v_and_b32_e32 v97, 0xffff0000, v149
	v_and_b32_e32 v96, 0xffff0000, v141
	v_add_f32_e32 v38, v150, v151
	v_lshlrev_b32_e32 v99, 16, v146
	v_lshlrev_b32_e32 v98, 16, v138
	v_lshlrev_b32_e32 v101, 16, v147
	v_lshlrev_b32_e32 v100, 16, v139
	v_lshlrev_b32_e32 v103, 16, v148
	v_lshlrev_b32_e32 v102, 16, v140
	v_lshlrev_b32_e32 v105, 16, v149
	v_lshlrev_b32_e32 v104, 16, v141
	v_pk_mul_f32 v[146:147], v[90:91], v[90:91]
	v_pk_mul_f32 v[148:149], v[92:93], v[92:93]
	v_pk_mul_f32 v[152:153], v[94:95], v[94:95]
	v_pk_mul_f32 v[154:155], v[96:97], v[96:97]
	ds_bpermute_b32 v40, v145, v38
	v_pk_fma_f32 v[146:147], v[98:99], v[98:99], v[146:147]
	v_pk_fma_f32 v[148:149], v[100:101], v[100:101], v[148:149]
	v_pk_fma_f32 v[152:153], v[102:103], v[102:103], v[152:153]
	v_pk_fma_f32 v[154:155], v[104:105], v[104:105], v[154:155]
	s_waitcnt lgkmcnt(2)
	v_add_f32_e32 v18, v18, v20
	v_pk_add_f32 v[146:147], v[146:147], v[148:149]
	v_pk_add_f32 v[148:149], v[152:153], v[154:155]
	ds_bpermute_b32 v20, v144, v18
	v_pk_add_f32 v[146:147], v[146:147], v[148:149]
	s_waitcnt lgkmcnt(2)
	v_add_f32_e32 v14, v14, v16
	v_add_f32_e32 v42, v146, v147
	ds_bpermute_b32 v44, v0, v14
	ds_bpermute_b32 v16, v145, v42
	s_waitcnt lgkmcnt(3)
	v_add_f32_e32 v38, v38, v40
	ds_bpermute_b32 v40, v144, v38
	s_waitcnt lgkmcnt(3)
	v_add_f32_e32 v18, v18, v20
	ds_bpermute_b32 v20, v143, v18
	s_waitcnt lgkmcnt(3)
	v_add_f32_e32 v14, v14, v44
	s_waitcnt lgkmcnt(2)
	v_add_f32_e32 v16, v42, v16
	v_fmamk_f32 v14, v14, 0x3a800000, v220
	ds_bpermute_b32 v42, v144, v16
	s_waitcnt lgkmcnt(2)
	v_add_f32_e32 v38, v38, v40
	v_mul_f32_e32 v40, 0x4f800000, v14
	v_cmp_gt_f32_e32 vcc, s45, v14
	ds_bpermute_b32 v44, v143, v38
	s_waitcnt lgkmcnt(2)
	v_add_f32_e32 v18, v18, v20
	v_cndmask_b32_e32 v14, v14, v40, vcc
	v_sqrt_f32_e32 v20, v14
	ds_bpermute_b32 v40, v142, v18
	s_waitcnt lgkmcnt(2)
	v_add_f32_e32 v16, v16, v42
	ds_bpermute_b32 v42, v143, v16
	s_waitcnt lgkmcnt(2)
	v_add_f32_e32 v38, v38, v44
	v_add_u32_e32 v44, -1, v20
	v_mov_b32_e32 v119, v48
	v_add_u32_e32 v46, 1, v20
	v_fma_f32 v48, -v44, v20, v14
	v_mov_b32_e32 v117, v50
	v_mov_b32_e32 v121, v52
	v_fma_f32 v50, -v46, v20, v14
	ds_bpermute_b32 v52, v142, v38
	v_cmp_ge_f32_e64 s[4:5], 0, v48
	s_waitcnt lgkmcnt(2)
	v_add_f32_e32 v18, v18, v40
	ds_bpermute_b32 v40, v5, v18
	v_cndmask_b32_e64 v20, v20, v44, s[4:5]
	v_cmp_lt_f32_e64 s[4:5], 0, v50
	s_waitcnt lgkmcnt(2)
	v_add_f32_e32 v16, v16, v42
	s_waitcnt lgkmcnt(1)
	v_add_f32_e32 v38, v38, v52
	v_cndmask_b32_e64 v20, v20, v46, s[4:5]
	v_mul_f32_e32 v42, 0x37800000, v20
	v_cndmask_b32_e32 v20, v20, v42, vcc
	v_cmp_class_f32_e32 vcc, v14, v221
	ds_bpermute_b32 v42, v142, v16
	s_waitcnt lgkmcnt(1)
; __device__ __forceinline__ unsigned cvtpk(float lo, float hi) { f32x2 v = {lo, hi}; bf16x2_t b = __builtin_convertvector(v, bf16x2_t); return __builtin_bit_cast(unsigned, b); }
; #define GAS __attribute__((address_space(1)))
; __device__ __forceinline__ f32x4 unpack_lo4(const u32x4 w) { return (f32x4){bf_lo(w.x), bf_hi(w.x), bf_lo(w.y), bf_hi(w.y)}; }
; __device__ __forceinline__ f32x4 unpack_hi4(const u32x4 w) { return (f32x4){bf_lo(w.z), bf_hi(w.z), bf_lo(w.w), bf_hi(w.w)}; }
; template <int R> __device__ __forceinline__ void norm_rows_bf16in(const bf16* x, bf16* o, int m0, int rstride, const float* g, const float* shift, const float* scale, int lane) {
;     ...
; #pragma unroll
;     for (int j = 0; j < 2; ++j) {
;         const int i4 = 2 * (lane + 64 * j);
;         const f32x4 g0 = ((const GAS f32x4*)g)[i4], g1 = ((const GAS f32x4*)g)[i4 + 1], h0 = ((const GAS f32x4*)shift)[i4], h1 = ((const GAS f32x4*)shift)[i4 + 1], c0 = ((const GAS f32x4*)scale)[i4], c1 = ((const GAS f32x4*)scale)[i4 + 1];
;         const f32x4 gs0 = g0 * (c0 + 1.0f), gs1 = g1 * (c1 + 1.0f);
; #pragma unroll
;         for (int r = 0; r < R; ++r) {
;             const float rstd = 1.0f / sqrtf(s[r] * (1.0f / D) + EPS);
;             const f32x4 y0 = unpack_lo4(v[r][j]) * rstd * gs0 + h0, y1 = unpack_hi4(v[r][j]) * rstd * gs1 + h1;
;             u32x4 w; w.x = cvtpk(y0.x, y0.y); w.y = cvtpk(y0.z, y0.w); w.z = cvtpk(y1.x, y1.y); w.w = cvtpk(y1.z, y1.w);
;             ((GAS u32x4*)(o + (size_t)(m0 + r * rstride) * D) + lane)[64 * j] = w;
;         }
	v_add_f32_e32 v18, v18, v40
	v_cndmask_b32_e32 v14, v20, v14, vcc
	ds_bpermute_b32 v20, v5, v38
	v_div_scale_f32 v44, s[4:5], v14, v14, 1.0
	v_rcp_f32_e32 v40, v44
	ds_bpermute_b32 v48, v0, v18
	s_waitcnt lgkmcnt(2)
	v_add_f32_e32 v16, v16, v42
	ds_bpermute_b32 v5, v5, v16
	s_waitcnt lgkmcnt(2)
	v_add_f32_e32 v20, v38, v20
	v_fma_f32 v38, -v44, v40, 1.0
	v_fmac_f32_e32 v40, v38, v40
	ds_bpermute_b32 v38, v0, v20
	v_div_scale_f32 v46, vcc, 1.0, v14, 1.0
	s_waitcnt lgkmcnt(2)
	v_add_f32_e32 v18, v18, v48
	v_mul_f32_e32 v42, v46, v40
	v_fmamk_f32 v18, v18, 0x3a800000, v220
	v_fma_f32 v48, -v44, v42, v46
	s_waitcnt lgkmcnt(1)
	v_add_f32_e32 v5, v16, v5
	v_mul_f32_e32 v16, 0x4f800000, v18
	v_cmp_gt_f32_e64 s[4:5], s45, v18
	v_fmac_f32_e32 v42, v48, v40
	v_fma_f32 v44, -v44, v42, v46
	v_cndmask_b32_e64 v16, v18, v16, s[4:5]
	ds_bpermute_b32 v18, v0, v5
	s_waitcnt lgkmcnt(1)
	v_add_f32_e32 v20, v20, v38
	v_sqrt_f32_e32 v38, v16
	v_div_fmas_f32 v0, v44, v40, v42
	v_div_fixup_f32 v0, v0, v14, 1.0
	v_fmamk_f32 v14, v20, 0x3a800000, v220
	v_mul_f32_e32 v20, 0x4f800000, v14
	v_cmp_gt_f32_e32 vcc, s45, v14
	s_waitcnt lgkmcnt(0)
	v_add_f32_e32 v5, v5, v18
	v_add_u32_e32 v18, -1, v38
	v_cndmask_b32_e32 v14, v14, v20, vcc
	v_pk_mul_f32 v[132:133], v[0:1], v[132:133] op_sel_hi:[0,1]
	v_pk_mul_f32 v[134:135], v[0:1], v[134:135] op_sel_hi:[0,1]
	v_pk_mul_f32 v[128:129], v[0:1], v[128:129] op_sel_hi:[0,1]
	v_pk_mul_f32 v[130:131], v[0:1], v[130:131] op_sel_hi:[0,1]
	v_add_u32_e32 v20, 1, v38
	v_sqrt_f32_e32 v40, v14
	v_fma_f32 v42, -v18, v38, v16
	v_pk_fma_f32 v[134:135], v[134:135], v[106:107], v[12:13]
	v_pk_fma_f32 v[132:133], v[132:133], v[108:109], v[10:11]
	v_pk_fma_f32 v[142:143], v[128:129], v[112:113], v[6:7]
	v_pk_fma_f32 v[144:145], v[130:131], v[110:111], v[8:9]
	v_fma_f32 v44, -v20, v38, v16
	v_cmp_ge_f32_e64 s[6:7], 0, v42
	v_cvt_pk_bf16_f32 v128, v132, v133
	v_cvt_pk_bf16_f32 v129, v134, v135
	v_cvt_pk_bf16_f32 v130, v142, v143
	v_cvt_pk_bf16_f32 v131, v144, v145
	v_fmamk_f32 v5, v5, 0x3a800000, v220
	v_cndmask_b32_e64 v18, v38, v18, s[6:7]
	v_cmp_lt_f32_e64 s[6:7], 0, v44
	global_store_dwordx4 v[26:27], v[128:131], off
	v_mul_f32_e32 v26, 0x4f800000, v5
	v_cmp_gt_f32_e64 s[8:9], s45, v5
	v_cndmask_b32_e64 v18, v18, v20, s[6:7]
	v_add_u32_e32 v20, -1, v40
	v_cndmask_b32_e64 v5, v5, v26, s[8:9]
	v_mul_f32_e32 v38, 0x37800000, v18
	v_add_u32_e32 v26, 1, v40
	v_sqrt_f32_e32 v27, v5
	v_cndmask_b32_e64 v18, v18, v38, s[4:5]
	v_fma_f32 v38, -v20, v40, v14
	v_fma_f32 v42, -v26, v40, v14
	v_cmp_ge_f32_e64 s[6:7], 0, v38
	v_cmp_class_f32_e64 s[4:5], v16, v221
	v_mov_b32_e32 v114, v54
	v_cndmask_b32_e64 v20, v40, v20, s[6:7]
	v_cmp_lt_f32_e64 s[6:7], 0, v42
	v_cndmask_b32_e64 v16, v18, v16, s[4:5]
	v_div_scale_f32 v18, s[4:5], v16, v16, 1.0
	v_cndmask_b32_e64 v20, v20, v26, s[6:7]
	v_add_u32_e32 v26, -1, v27
	v_mul_f32_e32 v44, 0x37800000, v20
	v_add_u32_e32 v40, 1, v27
	v_rcp_f32_e32 v42, v18
	v_cndmask_b32_e32 v20, v20, v44, vcc
	v_fma_f32 v44, -v26, v27, v5
	v_cmp_class_f32_e32 vcc, v14, v221
	v_fma_f32 v46, -v40, v27, v5
	v_cmp_ge_f32_e64 s[6:7], 0, v44
	v_cndmask_b32_e32 v14, v20, v14, vcc
	v_div_scale_f32 v20, s[10:11], v14, v14, 1.0
	v_cndmask_b32_e64 v26, v27, v26, s[6:7]
	v_cmp_lt_f32_e64 s[6:7], 0, v46
	v_fma_f32 v27, -v18, v42, 1.0
	v_rcp_f32_e32 v46, v20
	v_cndmask_b32_e64 v26, v26, v40, s[6:7]
	v_mul_f32_e32 v40, 0x37800000, v26
	v_div_scale_f32 v38, s[4:5], 1.0, v16, 1.0
	v_cndmask_b32_e64 v26, v26, v40, s[8:9]
	v_cmp_class_f32_e32 vcc, v5, v221
	v_fmac_f32_e32 v42, v27, v42
	v_mul_f32_e32 v27, v38, v42
	v_cndmask_b32_e32 v5, v26, v5, vcc
	v_fma_f32 v26, -v18, v27, v38
	v_div_scale_f32 v48, s[6:7], v5, v5, 1.0
	v_fmac_f32_e32 v27, v26, v42
	v_fma_f32 v26, -v20, v46, 1.0
	v_rcp_f32_e32 v52, v48
	v_div_scale_f32 v44, s[10:11], 1.0, v14, 1.0
	v_fmac_f32_e32 v46, v26, v46
	v_fma_f32 v18, -v18, v27, v38
	s_mov_b64 vcc, s[4:5]
	v_mul_f32_e32 v38, v44, v46
	v_div_fmas_f32 v18, v18, v42, v27
	v_fma_f32 v26, -v20, v38, v44
	v_div_fixup_f32 v40, v18, v16, 1.0
	v_fmac_f32_e32 v38, v26, v46
	v_fma_f32 v16, -v48, v52, 1.0
	v_mov_b32_e32 v118, v56
	v_mov_b32_e32 v116, v58
	v_mov_b32_e32 v120, v60
	v_div_scale_f32 v50, s[6:7], 1.0, v5, 1.0
	v_fma_f32 v18, -v20, v38, v44
	v_fmac_f32_e32 v52, v16, v52
	s_mov_b64 vcc, s[10:11]
	v_pk_mul_f32 v[26:27], v[40:41], v[118:119] op_sel_hi:[0,1]
	v_pk_mul_f32 v[114:115], v[40:41], v[114:115] op_sel_hi:[0,1]
	v_pk_mul_f32 v[116:117], v[40:41], v[116:117] op_sel_hi:[0,1]
	v_pk_mul_f32 v[118:119], v[40:41], v[120:121] op_sel_hi:[0,1]
	v_div_fmas_f32 v16, v18, v46, v38
	v_mul_f32_e32 v18, v50, v52
	v_pk_fma_f32 v[26:27], v[106:107], v[26:27], v[12:13]
	v_pk_fma_f32 v[114:115], v[108:109], v[114:115], v[10:11]
	v_pk_fma_f32 v[116:117], v[116:117], v[112:113], v[6:7]
	v_pk_fma_f32 v[118:119], v[118:119], v[110:111], v[8:9]
	v_fma_f32 v20, -v48, v18, v50
	v_mov_b32_e32 v122, v82
	v_mov_b32_e32 v123, v64
	v_mov_b32_e32 v126, v84
	v_mov_b32_e32 v127, v66
	v_mov_b32_e32 v124, v86
	v_mov_b32_e32 v125, v68
	v_mov_b32_e32 v136, v88
	v_mov_b32_e32 v137, v70
	v_cvt_pk_bf16_f32 v114, v114, v115
	v_cvt_pk_bf16_f32 v115, v26, v27
	v_cvt_pk_bf16_f32 v116, v116, v117
	v_cvt_pk_bf16_f32 v117, v118, v119
	v_div_fixup_f32 v42, v16, v14, 1.0
	v_fmac_f32_e32 v18, v20, v52
	global_store_dwordx4 v[32:33], v[114:117], off
	v_pk_mul_f32 v[26:27], v[42:43], v[126:127] op_sel_hi:[0,1]
	v_pk_mul_f32 v[118:119], v[42:43], v[136:137] op_sel_hi:[0,1]
; __device__ __forceinline__ unsigned cvtpk(float lo, float hi) { f32x2 v = {lo, hi}; bf16x2_t b = __builtin_convertvector(v, bf16x2_t); return __builtin_bit_cast(unsigned, b); }
; #define GAS __attribute__((address_space(1)))
; __device__ __forceinline__ f32x4 unpack_lo4(const u32x4 w) { return (f32x4){bf_lo(w.x), bf_hi(w.x), bf_lo(w.y), bf_hi(w.y)}; }
; __device__ __forceinline__ f32x4 unpack_hi4(const u32x4 w) { return (f32x4){bf_lo(w.z), bf_hi(w.z), bf_lo(w.w), bf_hi(w.w)}; }
; template <int R> __device__ __forceinline__ void norm_rows_bf16in(const bf16* x, bf16* o, int m0, int rstride, const float* g, const float* shift, const float* scale, int lane) {
;     ...
; #pragma unroll
;     for (int j = 0; j < 2; ++j) {
;         const int i4 = 2 * (lane + 64 * j);
;         const f32x4 g0 = ((const GAS f32x4*)g)[i4], g1 = ((const GAS f32x4*)g)[i4 + 1], h0 = ((const GAS f32x4*)shift)[i4], h1 = ((const GAS f32x4*)shift)[i4 + 1], c0 = ((const GAS f32x4*)scale)[i4], c1 = ((const GAS f32x4*)scale)[i4 + 1];
;         const f32x4 gs0 = g0 * (c0 + 1.0f), gs1 = g1 * (c1 + 1.0f);
; #pragma unroll
;         for (int r = 0; r < R; ++r) {
;             const float rstd = 1.0f / sqrtf(s[r] * (1.0f / D) + EPS);
;             const f32x4 y0 = unpack_lo4(v[r][j]) * rstd * gs0 + h0, y1 = unpack_hi4(v[r][j]) * rstd * gs1 + h1;
;             u32x4 w; w.x = cvtpk(y0.x, y0.y); w.y = cvtpk(y0.z, y0.w); w.z = cvtpk(y1.x, y1.y); w.w = cvtpk(y1.z, y1.w);
;             ((GAS u32x4*)(o + (size_t)(m0 + r * rstride) * D) + lane)[64 * j] = w;
;         }
	v_pk_mul_f32 v[114:115], v[42:43], v[122:123] op_sel_hi:[0,1]
	v_pk_mul_f32 v[116:117], v[42:43], v[124:125] op_sel_hi:[0,1]
	v_fma_f32 v14, -v48, v18, v50
	s_mov_b64 vcc, s[6:7]
	v_pk_fma_f32 v[26:27], v[106:107], v[26:27], v[12:13]
	v_pk_fma_f32 v[114:115], v[108:109], v[114:115], v[10:11]
	v_pk_fma_f32 v[116:117], v[112:113], v[116:117], v[6:7]
	v_pk_fma_f32 v[118:119], v[110:111], v[118:119], v[8:9]
	v_div_fmas_f32 v14, v14, v52, v18
	v_mov_b32_e32 v138, v100
	v_mov_b32_e32 v139, v92
	v_mov_b32_e32 v140, v98
	v_mov_b32_e32 v141, v90
	v_mov_b32_e32 v150, v102
	v_mov_b32_e32 v151, v94
	v_mov_b32_e32 v156, v104
	v_mov_b32_e32 v157, v96
	v_cvt_pk_bf16_f32 v114, v114, v115
	v_cvt_pk_bf16_f32 v115, v26, v27
	v_cvt_pk_bf16_f32 v116, v116, v117
	v_cvt_pk_bf16_f32 v117, v118, v119
	v_div_fixup_f32 v44, v14, v5, 1.0
	global_store_dwordx4 v[34:35], v[114:117], off
	v_pk_mul_f32 v[26:27], v[44:45], v[138:139] op_sel_hi:[0,1]
	v_pk_mul_f32 v[118:119], v[44:45], v[156:157] op_sel_hi:[0,1]
	v_pk_mul_f32 v[114:115], v[44:45], v[140:141] op_sel_hi:[0,1]
	v_pk_mul_f32 v[116:117], v[44:45], v[150:151] op_sel_hi:[0,1]
	v_pk_fma_f32 v[12:13], v[106:107], v[26:27], v[12:13]
	v_pk_fma_f32 v[10:11], v[108:109], v[114:115], v[10:11]
	v_pk_fma_f32 v[26:27], v[110:111], v[118:119], v[8:9]
	v_pk_fma_f32 v[8:9], v[112:113], v[116:117], v[6:7]
	v_cvt_pk_bf16_f32 v6, v10, v11
	v_cvt_pk_bf16_f32 v7, v12, v13
	v_cvt_pk_bf16_f32 v8, v8, v9
	v_cvt_pk_bf16_f32 v9, v26, v27
	global_store_dwordx4 v[36:37], v[6:9], off
	s_nop 1
	v_mov_b64_e32 v[6:7], v[160:161]
	v_mov_b64_e32 v[8:9], v[162:163]
	s_nop 0
	s_nop 1
	v_mov_b64_e32 v[10:11], v[164:165]
	v_mov_b64_e32 v[12:13], v[166:167]
	v_mov_b64_e32 v[106:107], v[168:169]
	v_mov_b64_e32 v[108:109], v[170:171]
	v_mov_b64_e32 v[110:111], v[172:173]
	v_mov_b64_e32 v[112:113], v[174:175]
	s_nop 0
	s_nop 1
	v_mov_b64_e32 v[24:25], v[176:177]
	v_mov_b64_e32 v[26:27], v[178:179]
	s_nop 0
	s_nop 1
	v_mov_b64_e32 v[28:29], v[180:181]
	v_mov_b64_e32 v[30:31], v[182:183]
	v_mov_b32_e32 v38, v41
	v_mov_b32_e32 v18, v43
	v_mov_b32_e32 v14, v45
	v_mov_b32_e32 v20, v47
	s_brev_b32 s4, 7
	v_mov_b32_e32 v16, v55
	v_mov_b32_e32 v48, v57
	v_mov_b32_e32 v50, v59
	v_mov_b32_e32 v52, v61
	v_mov_b32_e32 v64, v83
	v_mov_b32_e32 v66, v85
	v_mov_b32_e32 v68, v87
	v_mov_b32_e32 v70, v89
	v_mov_b32_e32 v90, v99
	v_mov_b32_e32 v92, v101
	v_mov_b32_e32 v94, v103
	v_mov_b32_e32 v96, v105
	v_pk_mul_f32 v[38:39], v[0:1], v[38:39] op_sel_hi:[0,1]
	v_pk_mul_f32 v[18:19], v[0:1], v[18:19] op_sel_hi:[0,1]
	v_pk_mul_f32 v[14:15], v[0:1], v[14:15] op_sel_hi:[0,1]
	v_pk_mul_f32 v[20:21], v[0:1], v[20:21] op_sel_hi:[0,1]
	s_mov_b32 s5, -1
	v_pk_mul_f32 v[16:17], v[40:41], v[16:17] op_sel_hi:[0,1]
	v_pk_mul_f32 v[46:47], v[40:41], v[48:49] op_sel_hi:[0,1]
	v_pk_mul_f32 v[48:49], v[40:41], v[50:51] op_sel_hi:[0,1]
	v_pk_mul_f32 v[40:41], v[40:41], v[52:53] op_sel_hi:[0,1]
	v_pk_mul_f32 v[50:51], v[42:43], v[64:65] op_sel_hi:[0,1]
	v_pk_mul_f32 v[52:53], v[42:43], v[66:67] op_sel_hi:[0,1]
	v_pk_mul_f32 v[54:55], v[42:43], v[68:69] op_sel_hi:[0,1]
	v_pk_mul_f32 v[42:43], v[42:43], v[70:71] op_sel_hi:[0,1]
	v_pk_mul_f32 v[56:57], v[44:45], v[90:91] op_sel_hi:[0,1]
	v_pk_mul_f32 v[58:59], v[44:45], v[92:93] op_sel_hi:[0,1]
	v_pk_mul_f32 v[60:61], v[44:45], v[94:95] op_sel_hi:[0,1]
	v_pk_mul_f32 v[44:45], v[44:45], v[96:97] op_sel_hi:[0,1]
	v_lshl_add_u64 v[22:23], v[22:23], 0, s[4:5]
	v_pk_add_f32 v[8:9], v[8:9], 1.0 op_sel_hi:[1,0]
	v_pk_add_f32 v[6:7], v[6:7], 1.0 op_sel_hi:[1,0]
	v_pk_add_f32 v[12:13], v[12:13], 1.0 op_sel_hi:[1,0]
	v_pk_add_f32 v[10:11], v[10:11], 1.0 op_sel_hi:[1,0]
	v_pk_mul_f32 v[8:9], v[108:109], v[8:9]
	v_pk_mul_f32 v[6:7], v[106:107], v[6:7]
	v_pk_mul_f32 v[12:13], v[112:113], v[12:13]
	v_pk_mul_f32 v[10:11], v[110:111], v[10:11]
	v_pk_fma_f32 v[18:19], v[18:19], v[8:9], v[26:27]
	v_pk_fma_f32 v[38:39], v[38:39], v[6:7], v[24:25]
	v_pk_fma_f32 v[20:21], v[20:21], v[12:13], v[30:31]
	v_pk_fma_f32 v[14:15], v[14:15], v[10:11], v[28:29]
	v_pk_fma_f32 v[46:47], v[46:47], v[8:9], v[26:27]
	v_pk_fma_f32 v[16:17], v[16:17], v[6:7], v[24:25]
	v_pk_fma_f32 v[40:41], v[40:41], v[12:13], v[30:31]
	v_pk_fma_f32 v[48:49], v[48:49], v[10:11], v[28:29]
	v_pk_fma_f32 v[52:53], v[52:53], v[8:9], v[26:27]
	v_pk_fma_f32 v[50:51], v[50:51], v[6:7], v[24:25]
	v_pk_fma_f32 v[42:43], v[42:43], v[12:13], v[30:31]
	v_pk_fma_f32 v[54:55], v[54:55], v[10:11], v[28:29]
	v_pk_fma_f32 v[26:27], v[58:59], v[8:9], v[26:27]
	v_pk_fma_f32 v[24:25], v[56:57], v[6:7], v[24:25]
	v_pk_fma_f32 v[30:31], v[44:45], v[12:13], v[30:31]
	v_pk_fma_f32 v[28:29], v[60:61], v[10:11], v[28:29]
	v_cvt_pk_bf16_f32 v6, v38, v39
	v_cvt_pk_bf16_f32 v7, v18, v19
	v_cvt_pk_bf16_f32 v8, v14, v15
	v_cvt_pk_bf16_f32 v9, v20, v21
	v_cvt_pk_bf16_f32 v10, v16, v17
	v_cvt_pk_bf16_f32 v11, v46, v47
	v_cvt_pk_bf16_f32 v12, v48, v49
	v_cvt_pk_bf16_f32 v13, v40, v41
	v_cvt_pk_bf16_f32 v14, v50, v51
	v_cvt_pk_bf16_f32 v15, v52, v53
	v_cvt_pk_bf16_f32 v16, v54, v55
	v_cvt_pk_bf16_f32 v17, v42, v43
	v_cvt_pk_bf16_f32 v18, v24, v25
	v_cvt_pk_bf16_f32 v19, v26, v27
	v_cvt_pk_bf16_f32 v20, v28, v29
	v_cvt_pk_bf16_f32 v21, v30, v31
	global_store_dwordx4 v[22:23], v[6:9], off offset:1024
	global_store_dwordx4 v[32:33], v[10:13], off offset:1024
	global_store_dwordx4 v[34:35], v[14:17], off offset:1024
	global_store_dwordx4 v[36:37], v[18:21], off offset:1024
	s_cbranch_scc1 .LBB0_124
	s_mov_b64 s[4:5], 0

; template <class T> __device__ __forceinline__ T* launder(T* p) { asm volatile("" : "+s"(p)); return p; }
; #define GAS __attribute__((address_space(1)))
; #define KARG(f) (kargp[opaque_zero()].f)
; template <int R> __device__ __forceinline__ void norm_rows_bf16(const float* x, bf16* o, int m0, int rstride, const float* g, const float* shift, const float* scale, int lane) {
;     f32x4 v[R][4]; float s[R];
; #pragma unroll
;     for (int r = 0; r < R; ++r) { const GAS f32x4* xr = (const GAS f32x4*)(x + (size_t)(m0 + r * rstride) * D) + lane;
; #pragma unroll
;         for (int j = 0; j < 4; ++j) v[r][j] = __builtin_nontemporal_load(xr + 64 * j); }
; #pragma unroll
;     for (int r = 0; r < R; ++r) { s[r] = 0.f;
; #pragma unroll
;         for (int j = 0; j < 4; ++j) s[r] += (v[r][j].x * v[r][j].x + v[r][j].y * v[r][j].y) + (v[r][j].z * v[r][j].z + v[r][j].w * v[r][j].w); }
; #pragma unroll
;     for (int of = 1; of < 64; of <<= 1) {
; #pragma unroll
;         for (int r = 0; r < R; ++r) s[r] += __shfl_xor(s[r], of); }
; #pragma unroll
;     for (int j = 0; j < 4; ++j) {
;         const f32x4 gg = ((const GAS f32x4*)g)[lane + 64 * j], sh = ((const GAS f32x4*)shift)[lane + 64 * j], sc = ((const GAS f32x4*)scale)[lane + 64 * j];
;         const f32x4 gs = gg * (sc + 1.0f);
; __global__ void __launch_bounds__(NWAVES * 64, 2) fwd_megakernel(Args a_unused) {
;     ...
;             if (step == 0) { const float* xin = launder(KARG(x));
;                 for (int it = 0, m = gw; it < M / (4 * NGW); ++it, m += 4 * NGW) {
;                     const float* mb = modl + (m >> 13) * NMOD + step * 3072;
;                     norm_rows_bf16<4>(xin, XNl, m, NGW, KARG(g_norm) + step * D, mb, mb + 1024, ln); }
.LBB0_128:
	s_add_i32 s4, s16, s14
	s_ashr_i32 s6, s4, 13
	s_mov_b32 s5, 0
	v_lshl_add_u64 v[6:7], s[74:75], 0, v[74:75]
	s_mulk_i32 s6, 0x2400
	global_load_dwordx4 v[58:61], v[6:7], off nt
	global_load_dwordx4 v[34:37], v[6:7], off offset:1024 nt
	global_load_dwordx4 v[22:25], v[6:7], off offset:2048 nt
	s_nop 0
	global_load_dwordx4 v[6:9], v[6:7], off offset:3072 nt
	s_ashr_i32 s7, s6, 31
	s_lshl_b64 s[6:7], s[6:7], 2
	s_add_u32 s6, s58, s6
	v_cmp_lt_i32_e32 vcc, v214, v213
	s_mul_hi_i32 s9, s5, 0xc8
	s_mulk_i32 s5, 0xc8
	s_addc_u32 s7, s59, s7
	v_cndmask_b32_e32 v0, v212, v214, vcc
	v_cmp_lt_i32_e32 vcc, v215, v213
	s_add_u32 s8, s0, s5
	s_addc_u32 s9, s1, s9
	v_cndmask_b32_e32 v5, v212, v215, vcc
	v_cmp_lt_i32_e32 vcc, v216, v213
	s_nop 0
	v_lshl_add_u64 v[88:89], s[6:7], 0, v[74:75]
	s_add_i32 s6, s4, 0x800
	v_cndmask_b32_e32 v10, v212, v216, vcc
	v_cmp_lt_i32_e32 vcc, v217, v213
	s_load_dwordx2 s[8:9], s[8:9], 0x20
	s_ashr_i32 s7, s6, 31
	v_cndmask_b32_e32 v11, v212, v217, vcc
	v_cmp_lt_i32_e32 vcc, v218, v213
	s_lshl_b64 s[10:11], s[6:7], 12
	v_lshlrev_b32_e32 v115, 2, v10
	v_cndmask_b32_e32 v12, v212, v218, vcc
	v_cmp_lt_i32_e32 vcc, v219, v213
	s_add_u32 s10, s72, s10
	v_lshlrev_b32_e32 v116, 2, v11
	v_cndmask_b32_e32 v13, v212, v219, vcc
	v_add_co_u32_e32 v10, vcc, s41, v88
	s_addc_u32 s11, s73, s11
	s_nop 0
	v_addc_co_u32_e32 v11, vcc, 0, v89, vcc
	global_load_dwordx4 v[50:53], v[88:89], off
	global_load_dwordx4 v[94:97], v[10:11], off
	s_add_i32 s20, s4, 0x1000
	v_lshl_add_u64 v[14:15], s[10:11], 0, v[74:75]
	s_waitcnt lgkmcnt(0)
	v_lshl_add_u64 v[92:93], s[8:9], 0, v[74:75]
	v_lshlrev_b32_e32 v117, 2, v12
	v_lshlrev_b32_e32 v118, 2, v13
	s_ashr_i32 s21, s20, 31
	global_load_dwordx4 v[70:73], v[14:15], off nt
	global_load_dwordx4 v[42:45], v[14:15], off offset:1024 nt
	global_load_dwordx4 v[10:13], v[14:15], off offset:3072 nt
	global_load_dwordx4 v[26:29], v[14:15], off offset:2048 nt
	global_load_dwordx4 v[98:101], v[92:93], off
	s_lshl_b64 s[10:11], s[20:21], 12
	s_add_u32 s8, s72, s10
	s_addc_u32 s9, s73, s11
	s_addk_i32 s4, 0x1800
	v_lshl_add_u64 v[14:15], s[8:9], 0, v[74:75]
	s_ashr_i32 s5, s4, 31
	global_load_dwordx4 v[66:69], v[14:15], off nt
	global_load_dwordx4 v[46:49], v[14:15], off offset:1024 nt
	global_load_dwordx4 v[30:33], v[14:15], off offset:2048 nt
	s_nop 0
	global_load_dwordx4 v[14:17], v[14:15], off offset:3072 nt
	s_lshl_b64 s[8:9], s[4:5], 12
	s_add_u32 s8, s72, s8
	s_addc_u32 s9, s73, s9
	v_lshl_add_u64 v[18:19], s[8:9], 0, v[74:75]
	global_load_dwordx4 v[62:65], v[18:19], off nt
	global_load_dwordx4 v[54:57], v[18:19], off offset:1024 nt
	global_load_dwordx4 v[38:41], v[18:19], off offset:2048 nt
	s_nop 0
	global_load_dwordx4 v[18:21], v[18:19], off offset:3072 nt
	v_lshlrev_b32_e32 v114, 2, v0
	v_lshlrev_b32_e32 v5, 2, v5
	s_lshl_b64 s[6:7], s[6:7], 11
	s_add_u32 s6, s62, s6
	v_lshlrev_b64 v[86:87], 3, v[2:3]
	s_addc_u32 s7, s63, s7
	s_lshl_b64 s[8:9], s[20:21], 11
	v_lshl_add_u64 v[82:83], s[6:7], 0, v[86:87]
	s_add_u32 s6, s62, s8
	s_addc_u32 s7, s63, s9
	s_lshl_b64 s[4:5], s[4:5], 11
	s_add_u32 s4, s62, s4
	s_addc_u32 s5, s63, s5
	v_lshl_add_u64 v[80:81], s[76:77], 0, v[86:87]
	v_lshl_add_u64 v[84:85], s[6:7], 0, v[86:87]
	v_lshl_add_u64 v[86:87], s[4:5], 0, v[86:87]
	v_lshl_add_u64 v[90:91], v[88:89], 0, s[48:49]
	global_load_dwordx4 v[160:163], v[90:91], off offset:1024
	global_load_dwordx4 v[164:167], v[92:93], off offset:1024
	global_load_dwordx4 v[168:171], v[88:89], off offset:1024
	global_load_dwordx4 v[172:175], v[90:91], off offset:2048
	global_load_dwordx4 v[176:179], v[92:93], off offset:2048
	global_load_dwordx4 v[180:183], v[88:89], off offset:2048
	global_load_dwordx4 v[184:187], v[90:91], off offset:3072
	global_load_dwordx4 v[188:191], v[92:93], off offset:3072
	global_load_dwordx4 v[192:195], v[88:89], off offset:3072
	s_addk_i32 s14, 0x2000
	s_add_u32 s76, s76, 0x1000000
	s_addc_u32 s77, s77, 0
	s_add_u32 s74, s74, 0x2000000
	s_waitcnt vmcnt(0)
	v_pk_mul_f32 v[102:103], v[60:61], v[60:61]
	v_pk_mul_f32 v[104:105], v[58:59], v[58:59]
	v_pk_mul_f32 v[106:107], v[36:37], v[36:37]
	v_pk_mul_f32 v[108:109], v[34:35], v[34:35]
	v_pk_mov_b32 v[112:113], v[104:105], v[102:103] op_sel:[1,0]
	v_mov_b32_e32 v105, v103
	v_pk_mov_b32 v[102:103], v[108:109], v[106:107] op_sel:[1,0]
	v_mov_b32_e32 v109, v107
	v_mul_f32_e32 v0, v23, v23
	v_mul_f32_e32 v110, v25, v25
	v_pk_add_f32 v[104:105], v[112:113], v[104:105]
	v_pk_add_f32 v[102:103], v[102:103], v[108:109]
	v_mul_f32_e32 v119, v8, v8
	v_mul_f32_e32 v120, v9, v9
	v_mul_f32_e32 v121, v6, v6
	v_mul_f32_e32 v122, v7, v7
	v_pk_fma_f32 v[106:107], v[22:23], v[22:23], v[0:1] op_sel_hi:[1,1,0]
	v_pk_fma_f32 v[110:111], v[24:25], v[24:25], v[110:111] op_sel_hi:[1,1,0]
	v_pk_add_f32 v[104:105], v[104:105], v[104:105] op_sel:[0,1] op_sel_hi:[1,0]
	v_pk_add_f32 v[102:103], v[102:103], v[102:103] op_sel:[0,1] op_sel_hi:[1,0]
	v_mov_b32_e32 v107, v119
	v_mov_b32_e32 v111, v120
	v_mov_b32_e32 v105, v121
	v_mov_b32_e32 v103, v122
	v_pk_add_f32 v[106:107], v[106:107], v[110:111]
	v_pk_add_f32 v[102:103], v[104:105], v[102:103]
	s_addc_u32 s75, s75, 0
	v_pk_add_f32 v[102:103], v[102:103], v[106:107]
	s_cmp_eq_u32 s14, 0x10000
	v_add_f32_e32 v113, v102, v103
	ds_bpermute_b32 v119, v114, v113
	s_waitcnt lgkmcnt(0)
	v_add_f32_e32 v119, v113, v119
	ds_bpermute_b32 v124, v5, v119
	v_pk_add_f32 v[96:97], v[96:97], 1.0 op_sel_hi:[1,0]
	v_pk_add_f32 v[102:103], v[94:95], 1.0 op_sel_hi:[1,0]
	s_waitcnt lgkmcnt(0)
; #define GAS __attribute__((address_space(1)))
; template <int R> __device__ __forceinline__ void norm_rows_bf16(const float* x, bf16* o, int m0, int rstride, const float* g, const float* shift, const float* scale, int lane) {
;     ...
;     for (int r = 0; r < R; ++r) { s[r] = 0.f;
; #pragma unroll
;         for (int j = 0; j < 4; ++j) s[r] += (v[r][j].x * v[r][j].x + v[r][j].y * v[r][j].y) + (v[r][j].z * v[r][j].z + v[r][j].w * v[r][j].w); }
; #pragma unroll
;     for (int of = 1; of < 64; of <<= 1) {
; #pragma unroll
;         for (int r = 0; r < R; ++r) s[r] += __shfl_xor(s[r], of); }
; #pragma unroll
;     for (int j = 0; j < 4; ++j) {
;         const f32x4 gg = ((const GAS f32x4*)g)[lane + 64 * j], sh = ((const GAS f32x4*)shift)[lane + 64 * j], sc = ((const GAS f32x4*)scale)[lane + 64 * j];
;         const f32x4 gs = gg * (sc + 1.0f);
; #pragma unroll
;         for (int r = 0; r < R; ++r) {
;             const float rstd = 1.0f / sqrtf(s[r] * (1.0f / D) + EPS);
	v_add_f32_e32 v119, v119, v124
	v_pk_mul_f32 v[104:105], v[72:73], v[72:73]
	v_pk_mul_f32 v[106:107], v[70:71], v[70:71]
	v_pk_mul_f32 v[108:109], v[44:45], v[44:45]
	v_pk_mul_f32 v[110:111], v[42:43], v[42:43]
	v_mul_f32_e32 v0, v27, v27
	v_mul_f32_e32 v112, v29, v29
	v_pk_mul_f32 v[94:95], v[100:101], v[96:97]
	v_pk_mul_f32 v[96:97], v[98:99], v[102:103]
	v_pk_mov_b32 v[98:99], v[106:107], v[104:105] op_sel:[1,0]
	v_mov_b32_e32 v107, v105
	v_pk_mov_b32 v[100:101], v[110:111], v[108:109] op_sel:[1,0]
	v_mov_b32_e32 v111, v109
	v_mul_f32_e32 v121, v12, v12
	v_mul_f32_e32 v122, v13, v13
	v_pk_fma_f32 v[102:103], v[26:27], v[26:27], v[0:1] op_sel_hi:[1,1,0]
	v_pk_fma_f32 v[104:105], v[28:29], v[28:29], v[112:113] op_sel_hi:[1,1,0]
	v_pk_add_f32 v[98:99], v[98:99], v[106:107]
	v_pk_add_f32 v[100:101], v[100:101], v[110:111]
	v_mul_f32_e32 v120, v10, v10
	v_mul_f32_e32 v123, v11, v11
	v_mov_b32_e32 v103, v121
	v_mov_b32_e32 v105, v122
	v_pk_add_f32 v[98:99], v[98:99], v[98:99] op_sel:[0,1] op_sel_hi:[1,0]
	v_pk_add_f32 v[100:101], v[100:101], v[100:101] op_sel:[0,1] op_sel_hi:[1,0]
	v_pk_add_f32 v[102:103], v[102:103], v[104:105]
	v_mov_b32_e32 v99, v120
	v_mov_b32_e32 v101, v123
	v_pk_mul_f32 v[104:105], v[68:69], v[68:69]
	v_pk_mul_f32 v[106:107], v[66:67], v[66:67]
	v_pk_mul_f32 v[108:109], v[48:49], v[48:49]
	v_pk_mul_f32 v[110:111], v[46:47], v[46:47]
	v_mul_f32_e32 v0, v31, v31
	v_mul_f32_e32 v112, v33, v33
	v_pk_add_f32 v[98:99], v[98:99], v[100:101]
	v_pk_mov_b32 v[100:101], v[106:107], v[104:105] op_sel:[1,0]
	v_mov_b32_e32 v107, v105
	v_pk_mov_b32 v[104:105], v[110:111], v[108:109] op_sel:[1,0]
	v_mov_b32_e32 v111, v109
	v_mul_f32_e32 v120, v16, v16
	v_mul_f32_e32 v121, v17, v17
	v_pk_fma_f32 v[108:109], v[30:31], v[30:31], v[0:1] op_sel_hi:[1,1,0]
	v_pk_fma_f32 v[112:113], v[32:33], v[32:33], v[112:113] op_sel_hi:[1,1,0]
	v_pk_add_f32 v[98:99], v[98:99], v[102:103]
	v_pk_add_f32 v[100:101], v[100:101], v[106:107]
	v_pk_add_f32 v[102:103], v[104:105], v[110:111]
	v_mul_f32_e32 v122, v14, v14
	v_mul_f32_e32 v123, v15, v15
	v_mov_b32_e32 v109, v120
	v_mov_b32_e32 v113, v121
	v_pk_add_f32 v[100:101], v[100:101], v[100:101] op_sel:[0,1] op_sel_hi:[1,0]
	v_pk_add_f32 v[102:103], v[102:103], v[102:103] op_sel:[0,1] op_sel_hi:[1,0]
	ds_bpermute_b32 v120, v115, v119
	v_pk_add_f32 v[104:105], v[108:109], v[112:113]
	v_add_f32_e32 v121, v98, v99
	v_mov_b32_e32 v101, v122
	v_mov_b32_e32 v103, v123
	v_pk_mul_f32 v[98:99], v[64:65], v[64:65]
	v_pk_mul_f32 v[106:107], v[62:63], v[62:63]
	v_pk_mul_f32 v[108:109], v[56:57], v[56:57]
	v_pk_mul_f32 v[110:111], v[54:55], v[54:55]
	ds_bpermute_b32 v126, v114, v121
	v_pk_add_f32 v[100:101], v[100:101], v[102:103]
	v_pk_mov_b32 v[102:103], v[106:107], v[98:99] op_sel:[1,0]
	v_mov_b32_e32 v107, v99
	v_pk_mov_b32 v[98:99], v[110:111], v[108:109] op_sel:[1,0]
	v_mov_b32_e32 v111, v109
	v_pk_add_f32 v[102:103], v[102:103], v[106:107]
	v_pk_add_f32 v[98:99], v[98:99], v[110:111]
	v_mul_f32_e32 v0, v39, v39
	v_mul_f32_e32 v112, v41, v41
	v_mul_f32_e32 v124, v18, v18
	v_mul_f32_e32 v125, v19, v19
	v_pk_add_f32 v[100:101], v[100:101], v[104:105]
	v_pk_add_f32 v[102:103], v[102:103], v[102:103] op_sel:[0,1] op_sel_hi:[1,0]
	v_pk_add_f32 v[98:99], v[98:99], v[98:99] op_sel:[0,1] op_sel_hi:[1,0]
	v_mul_f32_e32 v122, v20, v20
	v_mul_f32_e32 v123, v21, v21
	v_pk_fma_f32 v[108:109], v[38:39], v[38:39], v[0:1] op_sel_hi:[1,1,0]
	v_pk_fma_f32 v[112:113], v[40:41], v[40:41], v[112:113] op_sel_hi:[1,1,0]
	v_add_f32_e32 v0, v100, v101
	v_mov_b32_e32 v103, v124
	v_mov_b32_e32 v99, v125
	s_waitcnt lgkmcnt(1)
	v_add_f32_e32 v100, v119, v120
	v_mov_b32_e32 v109, v122
	v_mov_b32_e32 v113, v123
	v_pk_add_f32 v[98:99], v[102:103], v[98:99]
	ds_bpermute_b32 v102, v116, v100
	v_pk_add_f32 v[104:105], v[108:109], v[112:113]
	ds_bpermute_b32 v101, v114, v0
	s_waitcnt lgkmcnt(2)
	v_add_f32_e32 v103, v121, v126
	v_pk_add_f32 v[98:99], v[98:99], v[104:105]
	ds_bpermute_b32 v104, v5, v103
	v_add_f32_e32 v98, v98, v99
	ds_bpermute_b32 v99, v114, v98
	s_waitcnt lgkmcnt(3)
	v_add_f32_e32 v100, v100, v102
	s_waitcnt lgkmcnt(2)
	v_add_f32_e32 v0, v0, v101
	ds_bpermute_b32 v102, v117, v100
	ds_bpermute_b32 v101, v5, v0
	s_waitcnt lgkmcnt(3)
	v_add_f32_e32 v103, v103, v104
	ds_bpermute_b32 v104, v115, v103
	s_waitcnt lgkmcnt(3)
	v_add_f32_e32 v98, v98, v99
	ds_bpermute_b32 v5, v5, v98
	s_waitcnt lgkmcnt(3)
	v_add_f32_e32 v99, v100, v102
	s_waitcnt lgkmcnt(2)
	v_add_f32_e32 v0, v0, v101
	ds_bpermute_b32 v101, v118, v99
	s_waitcnt lgkmcnt(2)
	v_add_f32_e32 v102, v103, v104
	ds_bpermute_b32 v100, v115, v0
	ds_bpermute_b32 v103, v116, v102
	s_waitcnt lgkmcnt(3)
	v_add_f32_e32 v5, v98, v5
	ds_bpermute_b32 v98, v115, v5
	s_waitcnt lgkmcnt(3)
	v_add_f32_e32 v99, v99, v101
	v_fmamk_f32 v99, v99, 0x3a800000, v220
	s_waitcnt lgkmcnt(2)
	v_add_f32_e32 v0, v0, v100
	s_waitcnt lgkmcnt(1)
	v_add_f32_e32 v101, v102, v103
	v_mul_f32_e32 v102, 0x4f800000, v99
	v_cmp_gt_f32_e32 vcc, s45, v99
	ds_bpermute_b32 v100, v116, v0
	ds_bpermute_b32 v103, v117, v101
	v_cndmask_b32_e32 v99, v99, v102, vcc
	s_waitcnt lgkmcnt(2)
	v_add_f32_e32 v5, v5, v98
	v_sqrt_f32_e32 v98, v99
	ds_bpermute_b32 v102, v116, v5
	s_waitcnt lgkmcnt(2)
	v_add_f32_e32 v0, v0, v100
	s_waitcnt lgkmcnt(1)
	v_add_f32_e32 v101, v101, v103
	v_add_u32_e32 v103, -1, v98
	ds_bpermute_b32 v100, v117, v0
	v_add_u32_e32 v104, 1, v98
	v_fma_f32 v106, -v103, v98, v99
	ds_bpermute_b32 v105, v118, v101
	v_fma_f32 v107, -v104, v98, v99
	s_waitcnt lgkmcnt(2)
	v_add_f32_e32 v5, v5, v102
	v_cmp_ge_f32_e64 s[4:5], 0, v106
	ds_bpermute_b32 v102, v117, v5
	s_waitcnt lgkmcnt(2)
; __device__ __forceinline__ unsigned cvtpk(float lo, float hi) { f32x2 v = {lo, hi}; bf16x2_t b = __builtin_convertvector(v, bf16x2_t); return __builtin_bit_cast(unsigned, b); }
; #define GAS __attribute__((address_space(1)))
; template <int R> __device__ __forceinline__ void norm_rows_bf16(const float* x, bf16* o, int m0, int rstride, const float* g, const float* shift, const float* scale, int lane) {
;     ...
;     for (int j = 0; j < 4; ++j) {
;         const f32x4 gg = ((const GAS f32x4*)g)[lane + 64 * j], sh = ((const GAS f32x4*)shift)[lane + 64 * j], sc = ((const GAS f32x4*)scale)[lane + 64 * j];
;         const f32x4 gs = gg * (sc + 1.0f);
; #pragma unroll
;         for (int r = 0; r < R; ++r) {
;             const float rstd = 1.0f / sqrtf(s[r] * (1.0f / D) + EPS);
;             const f32x4 y = v[r][j] * rstd * gs + sh;
;             u32x2 w; w.x = cvtpk(y.x, y.y); w.y = cvtpk(y.z, y.w); ((GAS u32x2*)(o + (size_t)(m0 + r * rstride) * D) + lane)[64 * j] = w;
;         }
;     }
	v_add_f32_e32 v0, v0, v100
	v_cndmask_b32_e64 v98, v98, v103, s[4:5]
	v_cmp_lt_f32_e64 s[4:5], 0, v107
	ds_bpermute_b32 v100, v118, v0
	s_waitcnt lgkmcnt(2)
	v_add_f32_e32 v101, v101, v105
	v_cndmask_b32_e64 v98, v98, v104, s[4:5]
	v_mul_f32_e32 v103, 0x37800000, v98
	v_cndmask_b32_e32 v98, v98, v103, vcc
	v_cmp_class_f32_e32 vcc, v99, v221
	v_fmamk_f32 v101, v101, 0x3a800000, v220
	s_waitcnt lgkmcnt(1)
	v_add_f32_e32 v5, v5, v102
	v_cndmask_b32_e32 v98, v98, v99, vcc
	v_div_scale_f32 v102, s[4:5], v98, v98, 1.0
	v_mul_f32_e32 v99, 0x4f800000, v101
	v_cmp_gt_f32_e64 s[4:5], s45, v101
	v_rcp_f32_e32 v104, v102
	s_waitcnt lgkmcnt(0)
	v_add_f32_e32 v0, v0, v100
	v_cndmask_b32_e64 v99, v101, v99, s[4:5]
	v_sqrt_f32_e32 v105, v99
	ds_bpermute_b32 v101, v118, v5
	v_fmamk_f32 v0, v0, 0x3a800000, v220
	v_mul_f32_e32 v100, 0x4f800000, v0
	v_cmp_gt_f32_e64 s[6:7], s45, v0
	v_add_u32_e32 v106, -1, v105
	v_div_scale_f32 v103, vcc, 1.0, v98, 1.0
	v_cndmask_b32_e64 v100, v0, v100, s[6:7]
	v_fma_f32 v0, -v102, v104, 1.0
	v_add_u32_e32 v107, 1, v105
	v_sqrt_f32_e32 v108, v100
	v_fmac_f32_e32 v104, v0, v104
	v_fma_f32 v0, -v106, v105, v99
	s_waitcnt lgkmcnt(0)
	v_add_f32_e32 v5, v5, v101
	v_fma_f32 v101, -v107, v105, v99
	v_mul_f32_e32 v109, v103, v104
	v_cmp_ge_f32_e64 s[8:9], 0, v0
	v_fmamk_f32 v5, v5, 0x3a800000, v220
	v_cmp_gt_f32_e64 s[10:11], s45, v5
	v_cndmask_b32_e64 v0, v105, v106, s[8:9]
	v_cmp_lt_f32_e64 s[8:9], 0, v101
	v_fma_f32 v105, -v102, v109, v103
	v_mul_f32_e32 v101, 0x4f800000, v5
	v_fmac_f32_e32 v109, v105, v104
	v_cndmask_b32_e64 v0, v0, v107, s[8:9]
	v_cndmask_b32_e64 v5, v5, v101, s[10:11]
	v_add_u32_e32 v101, -1, v108
	v_fma_f32 v102, -v102, v109, v103
	v_mul_f32_e32 v103, 0x37800000, v0
	v_add_u32_e32 v105, 1, v108
	v_sqrt_f32_e32 v106, v5
	v_cndmask_b32_e64 v103, v0, v103, s[4:5]
	v_fma_f32 v0, -v101, v108, v100
	v_fma_f32 v107, -v105, v108, v100
	v_div_fmas_f32 v102, v102, v104, v109
	v_cmp_ge_f32_e32 vcc, 0, v0
	v_cmp_class_f32_e64 s[4:5], v99, v221
	v_div_fixup_f32 v0, v102, v98, 1.0
	v_cndmask_b32_e32 v101, v108, v101, vcc
	v_cmp_lt_f32_e32 vcc, 0, v107
	v_cndmask_b32_e64 v98, v103, v99, s[4:5]
	v_div_scale_f32 v99, s[4:5], v98, v98, 1.0
	v_cndmask_b32_e32 v101, v101, v105, vcc
	v_add_u32_e32 v103, -1, v106
	v_mul_f32_e32 v107, 0x37800000, v101
	v_pk_mul_f32 v[58:59], v[58:59], v[0:1] op_sel_hi:[1,0]
	v_pk_mul_f32 v[60:61], v[60:61], v[0:1] op_sel_hi:[1,0]
	v_add_u32_e32 v104, 1, v106
	v_rcp_f32_e32 v105, v99
	v_cndmask_b32_e64 v101, v101, v107, s[6:7]
	v_fma_f32 v107, -v103, v106, v5
	v_pk_fma_f32 v[60:61], v[94:95], v[60:61], v[52:53]
	v_pk_fma_f32 v[58:59], v[96:97], v[58:59], v[50:51]
	v_cmp_class_f32_e32 vcc, v100, v221
	v_fma_f32 v108, -v104, v106, v5
	v_cmp_ge_f32_e64 s[6:7], 0, v107
	v_cvt_pk_bf16_f32 v58, v58, v59
	v_cvt_pk_bf16_f32 v59, v60, v61
	v_cndmask_b32_e64 v60, v106, v103, s[6:7]
	v_cmp_lt_f32_e64 s[6:7], 0, v108
	v_cndmask_b32_e32 v100, v101, v100, vcc
	global_store_dwordx2 v[80:81], v[58:59], off
	v_div_scale_f32 v59, s[8:9], v100, v100, 1.0
	v_cndmask_b32_e64 v58, v60, v104, s[6:7]
	v_fma_f32 v60, -v99, v105, 1.0
	v_rcp_f32_e32 v103, v59
	v_mul_f32_e32 v61, 0x37800000, v58
	v_div_scale_f32 v102, s[4:5], 1.0, v98, 1.0
	v_cndmask_b32_e64 v58, v58, v61, s[10:11]
	v_cmp_class_f32_e32 vcc, v5, v221
	v_fmac_f32_e32 v105, v60, v105
	v_mul_f32_e32 v60, v102, v105
	v_cndmask_b32_e32 v5, v58, v5, vcc
	v_fma_f32 v58, -v99, v60, v102
	v_div_scale_f32 v104, s[6:7], v5, v5, 1.0
	v_fmac_f32_e32 v60, v58, v105
	v_fma_f32 v58, -v59, v103, 1.0
	v_rcp_f32_e32 v107, v104
	v_div_scale_f32 v101, s[8:9], 1.0, v100, 1.0
	v_fma_f32 v61, -v99, v60, v102
	v_fmac_f32_e32 v103, v58, v103
	s_mov_b64 vcc, s[4:5]
	v_div_fmas_f32 v58, v61, v105, v60
	v_mul_f32_e32 v99, v101, v103
	v_div_fixup_f32 v58, v58, v98, 1.0
	v_fma_f32 v98, -v59, v99, v101
	v_pk_mul_f32 v[60:61], v[70:71], v[58:59] op_sel_hi:[1,0]
	v_pk_mul_f32 v[70:71], v[72:73], v[58:59] op_sel_hi:[1,0]
	v_fmac_f32_e32 v99, v98, v103
	v_fma_f32 v72, -v104, v107, 1.0
	v_div_scale_f32 v106, s[6:7], 1.0, v5, 1.0
	v_fma_f32 v59, -v59, v99, v101
	v_fmac_f32_e32 v107, v72, v107
	s_mov_b64 vcc, s[8:9]
	v_pk_fma_f32 v[70:71], v[94:95], v[70:71], v[52:53]
	v_pk_fma_f32 v[60:61], v[96:97], v[60:61], v[50:51]
	v_div_fmas_f32 v59, v59, v103, v99
	v_mul_f32_e32 v72, v106, v107
	v_cvt_pk_bf16_f32 v60, v60, v61
	v_cvt_pk_bf16_f32 v61, v70, v71
	v_div_fixup_f32 v70, v59, v100, 1.0
	v_fma_f32 v59, -v104, v72, v106
	v_fmac_f32_e32 v72, v59, v107
	global_store_dwordx2 v[82:83], v[60:61], off
	v_pk_mul_f32 v[60:61], v[66:67], v[70:71] op_sel_hi:[1,0]
	v_pk_mul_f32 v[66:67], v[68:69], v[70:71] op_sel_hi:[1,0]
	v_fma_f32 v59, -v104, v72, v106
	s_mov_b64 vcc, s[6:7]
	v_pk_fma_f32 v[66:67], v[94:95], v[66:67], v[52:53]
	v_pk_fma_f32 v[60:61], v[96:97], v[60:61], v[50:51]
	v_div_fmas_f32 v59, v59, v107, v72
	v_cvt_pk_bf16_f32 v60, v60, v61
	v_cvt_pk_bf16_f32 v61, v66, v67
	v_div_fixup_f32 v68, v59, v5, 1.0
	global_store_dwordx2 v[84:85], v[60:61], off
	v_pk_mul_f32 v[60:61], v[62:63], v[68:69] op_sel_hi:[1,0]
	v_pk_mul_f32 v[62:63], v[64:65], v[68:69] op_sel_hi:[1,0]
	v_pk_fma_f32 v[50:51], v[96:97], v[60:61], v[50:51]
	v_pk_fma_f32 v[52:53], v[94:95], v[62:63], v[52:53]
	v_cvt_pk_bf16_f32 v50, v50, v51
	v_cvt_pk_bf16_f32 v51, v52, v53
	global_store_dwordx2 v[86:87], v[50:51], off
	s_nop 1
	v_mov_b64_e32 v[50:51], v[160:161]
	v_mov_b64_e32 v[52:53], v[162:163]
; __device__ __forceinline__ unsigned cvtpk(float lo, float hi) { f32x2 v = {lo, hi}; bf16x2_t b = __builtin_convertvector(v, bf16x2_t); return __builtin_bit_cast(unsigned, b); }
; #define GAS __attribute__((address_space(1)))
; template <int R> __device__ __forceinline__ void norm_rows_bf16(const float* x, bf16* o, int m0, int rstride, const float* g, const float* shift, const float* scale, int lane) {
;     ...
;     for (int j = 0; j < 4; ++j) {
;         const f32x4 gg = ((const GAS f32x4*)g)[lane + 64 * j], sh = ((const GAS f32x4*)shift)[lane + 64 * j], sc = ((const GAS f32x4*)scale)[lane + 64 * j];
;         const f32x4 gs = gg * (sc + 1.0f);
; #pragma unroll
;         for (int r = 0; r < R; ++r) {
;             const float rstd = 1.0f / sqrtf(s[r] * (1.0f / D) + EPS);
;             const f32x4 y = v[r][j] * rstd * gs + sh;
;             u32x2 w; w.x = cvtpk(y.x, y.y); w.y = cvtpk(y.z, y.w); ((GAS u32x2*)(o + (size_t)(m0 + r * rstride) * D) + lane)[64 * j] = w;
;         }
;     }
	s_nop 0
	s_nop 1
	v_mov_b64_e32 v[60:61], v[164:165]
	v_mov_b64_e32 v[62:63], v[166:167]
	v_mov_b64_e32 v[64:65], v[168:169]
	v_mov_b64_e32 v[66:67], v[170:171]
	v_pk_mul_f32 v[34:35], v[34:35], v[0:1] op_sel_hi:[1,0]
	v_pk_mul_f32 v[36:37], v[36:37], v[0:1] op_sel_hi:[1,0]
	v_pk_mul_f32 v[42:43], v[42:43], v[58:59] op_sel_hi:[1,0]
	v_pk_mul_f32 v[44:45], v[44:45], v[58:59] op_sel_hi:[1,0]
	v_pk_mul_f32 v[46:47], v[46:47], v[70:71] op_sel_hi:[1,0]
	v_pk_mul_f32 v[48:49], v[48:49], v[70:71] op_sel_hi:[1,0]
	v_pk_mul_f32 v[54:55], v[54:55], v[68:69] op_sel_hi:[1,0]
	v_pk_mul_f32 v[56:57], v[56:57], v[68:69] op_sel_hi:[1,0]
	v_pk_mul_f32 v[22:23], v[22:23], v[0:1] op_sel_hi:[1,0]
	v_pk_mul_f32 v[24:25], v[24:25], v[0:1] op_sel_hi:[1,0]
	v_pk_mul_f32 v[26:27], v[26:27], v[58:59] op_sel_hi:[1,0]
	v_pk_mul_f32 v[28:29], v[28:29], v[58:59] op_sel_hi:[1,0]
	v_pk_mul_f32 v[30:31], v[30:31], v[70:71] op_sel_hi:[1,0]
	v_pk_mul_f32 v[32:33], v[32:33], v[70:71] op_sel_hi:[1,0]
	v_pk_mul_f32 v[38:39], v[38:39], v[68:69] op_sel_hi:[1,0]
	v_pk_mul_f32 v[40:41], v[40:41], v[68:69] op_sel_hi:[1,0]
	v_pk_mul_f32 v[6:7], v[6:7], v[0:1] op_sel_hi:[1,0]
	v_pk_mul_f32 v[8:9], v[8:9], v[0:1] op_sel_hi:[1,0]
	v_pk_mul_f32 v[10:11], v[10:11], v[58:59] op_sel_hi:[1,0]
	v_pk_mul_f32 v[12:13], v[12:13], v[58:59] op_sel_hi:[1,0]
	v_pk_mul_f32 v[14:15], v[14:15], v[70:71] op_sel_hi:[1,0]
	v_pk_mul_f32 v[16:17], v[16:17], v[70:71] op_sel_hi:[1,0]
	v_pk_mul_f32 v[18:19], v[18:19], v[68:69] op_sel_hi:[1,0]
	v_pk_mul_f32 v[20:21], v[20:21], v[68:69] op_sel_hi:[1,0]
	v_pk_add_f32 v[52:53], v[52:53], 1.0 op_sel_hi:[1,0]
	v_pk_add_f32 v[50:51], v[50:51], 1.0 op_sel_hi:[1,0]
	v_pk_mul_f32 v[52:53], v[62:63], v[52:53]
	v_pk_mul_f32 v[50:51], v[60:61], v[50:51]
	v_pk_fma_f32 v[36:37], v[36:37], v[52:53], v[66:67]
	v_pk_fma_f32 v[34:35], v[34:35], v[50:51], v[64:65]
	v_pk_fma_f32 v[44:45], v[44:45], v[52:53], v[66:67]
	v_pk_fma_f32 v[48:49], v[48:49], v[52:53], v[66:67]
	v_pk_fma_f32 v[52:53], v[56:57], v[52:53], v[66:67]
	v_pk_fma_f32 v[42:43], v[42:43], v[50:51], v[64:65]
	v_pk_fma_f32 v[46:47], v[46:47], v[50:51], v[64:65]
	v_pk_fma_f32 v[50:51], v[54:55], v[50:51], v[64:65]
	v_cvt_pk_bf16_f32 v34, v34, v35
	v_cvt_pk_bf16_f32 v35, v36, v37
	v_cvt_pk_bf16_f32 v36, v42, v43
	v_cvt_pk_bf16_f32 v37, v44, v45
	v_cvt_pk_bf16_f32 v42, v46, v47
	v_cvt_pk_bf16_f32 v43, v48, v49
	v_cvt_pk_bf16_f32 v44, v50, v51
	v_cvt_pk_bf16_f32 v45, v52, v53
	global_store_dwordx2 v[80:81], v[34:35], off offset:512
	global_store_dwordx2 v[82:83], v[36:37], off offset:512
	global_store_dwordx2 v[84:85], v[42:43], off offset:512
	global_store_dwordx2 v[86:87], v[44:45], off offset:512
	s_nop 1
	v_mov_b64_e32 v[34:35], v[172:173]
	v_mov_b64_e32 v[36:37], v[174:175]
	s_nop 0
	s_nop 1
	v_mov_b64_e32 v[42:43], v[176:177]
	v_mov_b64_e32 v[44:45], v[178:179]
	v_mov_b64_e32 v[46:47], v[180:181]
	v_mov_b64_e32 v[48:49], v[182:183]
	v_pk_add_f32 v[36:37], v[36:37], 1.0 op_sel_hi:[1,0]
	v_pk_add_f32 v[34:35], v[34:35], 1.0 op_sel_hi:[1,0]
	v_pk_mul_f32 v[36:37], v[44:45], v[36:37]
	v_pk_mul_f32 v[34:35], v[42:43], v[34:35]
	v_pk_fma_f32 v[24:25], v[24:25], v[36:37], v[48:49]
	v_pk_fma_f32 v[22:23], v[22:23], v[34:35], v[46:47]
	v_pk_fma_f32 v[28:29], v[28:29], v[36:37], v[48:49]
	v_pk_fma_f32 v[32:33], v[32:33], v[36:37], v[48:49]
	v_pk_fma_f32 v[36:37], v[40:41], v[36:37], v[48:49]
	v_pk_fma_f32 v[26:27], v[26:27], v[34:35], v[46:47]
	v_pk_fma_f32 v[30:31], v[30:31], v[34:35], v[46:47]
	v_pk_fma_f32 v[34:35], v[38:39], v[34:35], v[46:47]
	v_cvt_pk_bf16_f32 v22, v22, v23
	v_cvt_pk_bf16_f32 v23, v24, v25
	v_cvt_pk_bf16_f32 v24, v26, v27
	v_cvt_pk_bf16_f32 v25, v28, v29
	v_cvt_pk_bf16_f32 v26, v30, v31
	v_cvt_pk_bf16_f32 v27, v32, v33
	v_cvt_pk_bf16_f32 v28, v34, v35
	v_cvt_pk_bf16_f32 v29, v36, v37
	global_store_dwordx2 v[80:81], v[22:23], off offset:1024
	global_store_dwordx2 v[82:83], v[24:25], off offset:1024
	global_store_dwordx2 v[84:85], v[26:27], off offset:1024
	global_store_dwordx2 v[86:87], v[28:29], off offset:1024
	s_nop 1
	v_mov_b64_e32 v[22:23], v[184:185]
	v_mov_b64_e32 v[24:25], v[186:187]
	s_nop 0
	s_nop 1
	v_mov_b64_e32 v[26:27], v[188:189]
	v_mov_b64_e32 v[28:29], v[190:191]
	v_mov_b64_e32 v[30:31], v[192:193]
	v_mov_b64_e32 v[32:33], v[194:195]
	v_pk_add_f32 v[24:25], v[24:25], 1.0 op_sel_hi:[1,0]
	v_pk_add_f32 v[22:23], v[22:23], 1.0 op_sel_hi:[1,0]
	v_pk_mul_f32 v[24:25], v[28:29], v[24:25]
	v_pk_mul_f32 v[22:23], v[26:27], v[22:23]
	v_pk_fma_f32 v[8:9], v[8:9], v[24:25], v[32:33]
	v_pk_fma_f32 v[6:7], v[6:7], v[22:23], v[30:31]
	v_pk_fma_f32 v[12:13], v[12:13], v[24:25], v[32:33]
	v_pk_fma_f32 v[10:11], v[10:11], v[22:23], v[30:31]
	v_pk_fma_f32 v[16:17], v[16:17], v[24:25], v[32:33]
	v_pk_fma_f32 v[14:15], v[14:15], v[22:23], v[30:31]
	v_pk_fma_f32 v[20:21], v[20:21], v[24:25], v[32:33]
	v_pk_fma_f32 v[18:19], v[18:19], v[22:23], v[30:31]
	v_cvt_pk_bf16_f32 v6, v6, v7
	v_cvt_pk_bf16_f32 v7, v8, v9
	v_cvt_pk_bf16_f32 v8, v10, v11
	v_cvt_pk_bf16_f32 v9, v12, v13
	v_cvt_pk_bf16_f32 v10, v14, v15
	v_cvt_pk_bf16_f32 v11, v16, v17
	v_cvt_pk_bf16_f32 v12, v18, v19
	v_cvt_pk_bf16_f32 v13, v20, v21
	global_store_dwordx2 v[80:81], v[6:7], off offset:1536
	global_store_dwordx2 v[82:83], v[8:9], off offset:1536
	global_store_dwordx2 v[84:85], v[10:11], off offset:1536
	global_store_dwordx2 v[86:87], v[12:13], off offset:1536
	s_cbranch_scc0 .LBB0_128
	s_branch .LBB0_119
